# last down-projection epilogue: residual rows of groups 1-7 loaded up front so waits no longer serialize behind the write-through partial-sum stores (on top of v17)
# speedup vs baseline: 1.0190x; 1.0025x over previous
.LBB0_1934:
	v_mov_b32_e32 v156, v178
	v_mov_b32_e32 v164, v179
	s_lshl_b32 s27, s59, 8
	v_add_u32_e32 v185, s49, v156
	s_lshl_b32 s16, s26, 8
	v_add_u32_e32 v144, s27, v185
	s_or_b32 s16, s16, s50
	v_ashrrev_i32_e32 v145, 31, v144
	v_lshl_add_u32 v146, v164, 3, s16
	v_lshlrev_b64 v[148:149], 11, v[144:145]
	v_ashrrev_i32_e32 v147, 31, v146
	v_lshl_add_u64 v[148:149], s[14:15], 0, v[148:149]
	v_lshl_add_u64 v[152:153], v[146:147], 1, v[148:149]
	s_mov_b32 s90, 0x8000
	s_mov_b32 s91, 0
	s_mov_b32 s92, 0x28000
	s_mov_b32 s93, 0
	v_lshl_add_u64 v[254:255], v[152:153], 0, s[90:91]
	global_load_dwordx4 v[194:197], v[254:255], off
	global_load_dwordx4 v[198:201], v[254:255], off offset:256
	v_lshl_add_u64 v[254:255], v[254:255], 0, s[90:91]
	global_load_dwordx4 v[202:205], v[254:255], off
	global_load_dwordx4 v[206:209], v[254:255], off offset:256
	v_lshl_add_u64 v[254:255], v[254:255], 0, s[90:91]
	global_load_dwordx4 v[210:213], v[254:255], off
	global_load_dwordx4 v[214:217], v[254:255], off offset:256
	v_lshl_add_u64 v[254:255], v[254:255], 0, s[92:93]
	global_load_dwordx4 v[218:221], v[254:255], off
	global_load_dwordx4 v[226:229], v[254:255], off offset:256
	v_lshl_add_u64 v[254:255], v[254:255], 0, s[90:91]
	global_load_dwordx4 v[230:233], v[254:255], off
	global_load_dwordx4 v[234:237], v[254:255], off offset:256
	v_lshl_add_u64 v[254:255], v[254:255], 0, s[90:91]
	global_load_dwordx4 v[238:241], v[254:255], off
	global_load_dwordx4 v[242:245], v[254:255], off offset:256
	v_lshl_add_u64 v[254:255], v[254:255], 0, s[90:91]
	global_load_dwordx4 v[246:249], v[254:255], off
	global_load_dwordx4 v[180:183], v[254:255], off offset:256
	global_load_dwordx4 v[148:151], v[152:153], off
	s_nop 0
	global_load_dwordx4 v[152:155], v[152:153], off offset:256
	v_lshlrev_b32_e32 v156, 2, v156
	v_lshl_add_u32 v165, v164, 6, v156
	v_xor_b32_e32 v186, 64, v165
	v_xor_b32_e32 v187, 0x80, v165
	s_lshl_b32 s34, s26, 2
	v_cmp_eq_u32_e32 vcc, 0, v164
	s_ashr_i32 s35, s34, 31
	s_waitcnt vmcnt(0)
	v_lshlrev_b32_e32 v156, 16, v148
	v_and_b32_e32 v157, 0xffff0000, v148
	v_lshlrev_b32_e32 v148, 16, v149
	v_and_b32_e32 v149, 0xffff0000, v149
	v_lshlrev_b32_e32 v158, 16, v150
	v_and_b32_e32 v159, 0xffff0000, v150
	v_lshlrev_b32_e32 v150, 16, v151
	v_and_b32_e32 v151, 0xffff0000, v151
	v_lshlrev_b32_e32 v160, 16, v152
	v_and_b32_e32 v161, 0xffff0000, v152
	v_lshlrev_b32_e32 v152, 16, v153
	v_and_b32_e32 v153, 0xffff0000, v153
	v_lshlrev_b32_e32 v162, 16, v154
	v_and_b32_e32 v163, 0xffff0000, v154
	v_lshlrev_b32_e32 v154, 16, v155
	v_and_b32_e32 v155, 0xffff0000, v155
	v_pk_add_f32 v[126:127], v[126:127], v[148:149]
	v_pk_add_f32 v[124:125], v[124:125], v[156:157]
	v_pk_add_f32 v[122:123], v[122:123], v[150:151]
	v_pk_add_f32 v[120:121], v[120:121], v[158:159]
	v_pk_add_f32 v[118:119], v[118:119], v[152:153]
	v_pk_add_f32 v[116:117], v[116:117], v[160:161]
	v_pk_add_f32 v[114:115], v[114:115], v[154:155]
	v_pk_add_f32 v[112:113], v[112:113], v[162:163]
	v_mul_f32_e32 v148, v125, v125
	v_mul_f32_e32 v149, v127, v127
	v_mul_f32_e32 v150, v121, v121
	v_mul_f32_e32 v151, v123, v123
	v_mul_f32_e32 v152, v117, v117
	v_mul_f32_e32 v153, v119, v119
	v_mul_f32_e32 v154, v113, v113
	v_mul_f32_e32 v155, v115, v115
	v_fmac_f32_e32 v148, v124, v124
	v_fmac_f32_e32 v149, v126, v126
	v_fmac_f32_e32 v150, v120, v120
	v_fmac_f32_e32 v151, v122, v122
	v_fmac_f32_e32 v152, v116, v116
	v_fmac_f32_e32 v153, v118, v118
	v_fmac_f32_e32 v154, v112, v112
	v_fmac_f32_e32 v155, v114, v114
	v_add_f32_e32 v148, v148, v149
	v_add_f32_e32 v149, v150, v151
	v_add_f32_e32 v150, v152, v153
	v_add_f32_e32 v151, v154, v155
	v_add_f32_e32 v148, v148, v149
	v_add_f32_e32 v149, v150, v151
	v_add_f32_e32 v148, v148, v149
	ds_bpermute_b32 v149, v186, v148
	s_waitcnt lgkmcnt(0)
	v_add_f32_e32 v148, v148, v149
	ds_bpermute_b32 v149, v187, v148
	s_and_saveexec_b64 s[36:37], vcc
	s_cbranch_execz .LBB0_1936
	v_lshlrev_b64 v[150:151], 6, v[144:145]
	v_lshl_add_u64 v[150:151], s[12:13], 0, v[150:151]
	v_lshl_add_u64 v[150:151], s[34:35], 2, v[150:151]
	s_lshl_b32 s16, s48, 2
	v_lshl_add_u64 v[150:151], v[150:151], 0, s[16:17]
	s_waitcnt lgkmcnt(0)
	v_add_f32_e32 v148, v148, v149
	global_store_dword v[150:151], v148, off sc1
.LBB0_1936:
	s_or_b64 exec, exec, s[36:37]
	v_add_u32_e32 v148, 16, v144
	s_waitcnt lgkmcnt(0)
	v_ashrrev_i32_e32 v149, 31, v148
	v_lshlrev_b64 v[150:151], 11, v[148:149]
	v_lshl_add_u64 v[150:151], s[14:15], 0, v[150:151]
	v_lshl_add_u64 v[154:155], v[146:147], 1, v[150:151]
	s_nop 0
	s_waitcnt vmcnt(15)
	v_mov_b32_e32 v150, v194
	v_mov_b32_e32 v151, v195
	v_mov_b32_e32 v152, v196
	v_mov_b32_e32 v153, v197
	v_lshlrev_b32_e32 v158, 16, v150
	v_and_b32_e32 v159, 0xffff0000, v150
	v_lshlrev_b32_e32 v150, 16, v151
	v_and_b32_e32 v151, 0xffff0000, v151
	v_lshlrev_b32_e32 v160, 16, v152
	v_and_b32_e32 v161, 0xffff0000, v152
	v_lshlrev_b32_e32 v152, 16, v153
	v_and_b32_e32 v153, 0xffff0000, v153
	v_mov_b32_e32 v154, v198
	v_mov_b32_e32 v155, v199
	v_mov_b32_e32 v156, v200
	v_mov_b32_e32 v157, v201
	v_lshlrev_b32_e32 v162, 16, v154
	v_and_b32_e32 v163, 0xffff0000, v154
	v_lshlrev_b32_e32 v154, 16, v155
	v_and_b32_e32 v155, 0xffff0000, v155
	v_lshlrev_b32_e32 v164, 16, v156
	v_and_b32_e32 v165, 0xffff0000, v156
	v_lshlrev_b32_e32 v156, 16, v157
	v_and_b32_e32 v157, 0xffff0000, v157
	v_pk_add_f32 v[110:111], v[110:111], v[150:151]
	v_pk_add_f32 v[108:109], v[108:109], v[158:159]
	v_pk_add_f32 v[106:107], v[106:107], v[152:153]
	v_pk_add_f32 v[104:105], v[104:105], v[160:161]
	v_pk_add_f32 v[102:103], v[102:103], v[154:155]
	v_pk_add_f32 v[100:101], v[100:101], v[162:163]
	v_pk_add_f32 v[98:99], v[98:99], v[156:157]
	v_pk_add_f32 v[96:97], v[96:97], v[164:165]
	v_mul_f32_e32 v150, v109, v109
	v_mul_f32_e32 v151, v111, v111
	v_mul_f32_e32 v152, v105, v105
	v_mul_f32_e32 v153, v107, v107
	v_mul_f32_e32 v154, v101, v101
	v_mul_f32_e32 v155, v103, v103
	v_mul_f32_e32 v156, v97, v97
	v_mul_f32_e32 v157, v99, v99
	v_fmac_f32_e32 v150, v108, v108
	v_fmac_f32_e32 v151, v110, v110
	v_fmac_f32_e32 v152, v104, v104
	v_fmac_f32_e32 v153, v106, v106
	v_fmac_f32_e32 v154, v100, v100
	v_fmac_f32_e32 v155, v102, v102
	v_fmac_f32_e32 v156, v96, v96
	v_fmac_f32_e32 v157, v98, v98
	v_add_f32_e32 v150, v150, v151
	v_add_f32_e32 v151, v152, v153
	v_add_f32_e32 v152, v154, v155
	v_add_f32_e32 v153, v156, v157
	v_add_f32_e32 v150, v150, v151
	v_add_f32_e32 v151, v152, v153
	v_add_f32_e32 v150, v150, v151
	ds_bpermute_b32 v151, v186, v150
	s_waitcnt lgkmcnt(0)
	v_add_f32_e32 v150, v150, v151
	ds_bpermute_b32 v151, v187, v150
	s_and_saveexec_b64 s[36:37], vcc
	s_cbranch_execz .LBB0_1938
	v_lshlrev_b64 v[152:153], 6, v[148:149]
	v_lshl_add_u64 v[152:153], s[12:13], 0, v[152:153]
	v_lshl_add_u64 v[152:153], s[34:35], 2, v[152:153]
	s_lshl_b32 s16, s48, 2
	v_lshl_add_u64 v[152:153], v[152:153], 0, s[16:17]
	s_waitcnt lgkmcnt(0)
	v_add_f32_e32 v150, v150, v151
	global_store_dword v[152:153], v150, off sc1
.LBB0_1938:
	s_or_b64 exec, exec, s[36:37]
	v_add_u32_e32 v150, 32, v144
	s_waitcnt lgkmcnt(0)
	v_ashrrev_i32_e32 v151, 31, v150
	v_lshlrev_b64 v[152:153], 11, v[150:151]
	v_lshl_add_u64 v[152:153], s[14:15], 0, v[152:153]
	v_lshl_add_u64 v[156:157], v[146:147], 1, v[152:153]
	s_nop 0
	s_waitcnt vmcnt(15)
	v_mov_b32_e32 v152, v202
	v_mov_b32_e32 v153, v203
	v_mov_b32_e32 v154, v204
	v_mov_b32_e32 v155, v205
	v_lshlrev_b32_e32 v160, 16, v152
	v_and_b32_e32 v161, 0xffff0000, v152
	v_lshlrev_b32_e32 v152, 16, v153
	v_and_b32_e32 v153, 0xffff0000, v153
	v_lshlrev_b32_e32 v162, 16, v154
	v_and_b32_e32 v163, 0xffff0000, v154
	v_lshlrev_b32_e32 v154, 16, v155
	v_and_b32_e32 v155, 0xffff0000, v155
	v_mov_b32_e32 v156, v206
	v_mov_b32_e32 v157, v207
	v_mov_b32_e32 v158, v208
	v_mov_b32_e32 v159, v209
	v_lshlrev_b32_e32 v164, 16, v156
	v_and_b32_e32 v165, 0xffff0000, v156
	v_lshlrev_b32_e32 v156, 16, v157
	v_and_b32_e32 v157, 0xffff0000, v157
	v_lshlrev_b32_e32 v166, 16, v158
	v_and_b32_e32 v167, 0xffff0000, v158
	v_lshlrev_b32_e32 v158, 16, v159
	v_and_b32_e32 v159, 0xffff0000, v159
	v_pk_add_f32 v[94:95], v[94:95], v[152:153]
	v_pk_add_f32 v[92:93], v[92:93], v[160:161]
	v_pk_add_f32 v[90:91], v[90:91], v[154:155]
	v_pk_add_f32 v[88:89], v[88:89], v[162:163]
	v_pk_add_f32 v[86:87], v[86:87], v[156:157]
	v_pk_add_f32 v[84:85], v[84:85], v[164:165]
	v_pk_add_f32 v[82:83], v[82:83], v[158:159]
	v_pk_add_f32 v[80:81], v[80:81], v[166:167]
	v_mul_f32_e32 v152, v93, v93
	v_mul_f32_e32 v153, v95, v95
	v_mul_f32_e32 v154, v89, v89
	v_mul_f32_e32 v155, v91, v91
	v_mul_f32_e32 v156, v85, v85
	v_mul_f32_e32 v157, v87, v87
	v_mul_f32_e32 v158, v81, v81
	v_mul_f32_e32 v159, v83, v83
	v_fmac_f32_e32 v152, v92, v92
	v_fmac_f32_e32 v153, v94, v94
	v_fmac_f32_e32 v154, v88, v88
	v_fmac_f32_e32 v155, v90, v90
	v_fmac_f32_e32 v156, v84, v84
	v_fmac_f32_e32 v157, v86, v86
	v_fmac_f32_e32 v158, v80, v80
	v_fmac_f32_e32 v159, v82, v82
	v_add_f32_e32 v152, v152, v153
	v_add_f32_e32 v153, v154, v155
	v_add_f32_e32 v154, v156, v157
	v_add_f32_e32 v155, v158, v159
	v_add_f32_e32 v152, v152, v153
	v_add_f32_e32 v153, v154, v155
	v_add_f32_e32 v152, v152, v153
	ds_bpermute_b32 v153, v186, v152
	s_waitcnt lgkmcnt(0)
	v_add_f32_e32 v152, v152, v153
	ds_bpermute_b32 v153, v187, v152
	s_and_saveexec_b64 s[36:37], vcc
	s_cbranch_execz .LBB0_1940
	v_lshlrev_b64 v[154:155], 6, v[150:151]
	v_lshl_add_u64 v[154:155], s[12:13], 0, v[154:155]
	v_lshl_add_u64 v[154:155], s[34:35], 2, v[154:155]
	s_lshl_b32 s16, s48, 2
	v_lshl_add_u64 v[154:155], v[154:155], 0, s[16:17]
	s_waitcnt lgkmcnt(0)
	v_add_f32_e32 v152, v152, v153
	global_store_dword v[154:155], v152, off sc1
.LBB0_1940:
	s_or_b64 exec, exec, s[36:37]
	v_add_u32_e32 v152, 48, v144
	s_waitcnt lgkmcnt(0)
	v_ashrrev_i32_e32 v153, 31, v152
	v_lshlrev_b64 v[154:155], 11, v[152:153]
	v_lshl_add_u64 v[154:155], s[14:15], 0, v[154:155]
	v_lshl_add_u64 v[158:159], v[146:147], 1, v[154:155]
	s_nop 0
	s_waitcnt vmcnt(15)
	v_mov_b32_e32 v154, v210
	v_mov_b32_e32 v155, v211
	v_mov_b32_e32 v156, v212
	v_mov_b32_e32 v157, v213
	v_lshlrev_b32_e32 v162, 16, v154
	v_and_b32_e32 v163, 0xffff0000, v154
	v_lshlrev_b32_e32 v154, 16, v155
	v_and_b32_e32 v155, 0xffff0000, v155
	v_lshlrev_b32_e32 v164, 16, v156
	v_and_b32_e32 v165, 0xffff0000, v156
	v_lshlrev_b32_e32 v156, 16, v157
	v_and_b32_e32 v157, 0xffff0000, v157
	v_mov_b32_e32 v158, v214
	v_mov_b32_e32 v159, v215
	v_mov_b32_e32 v160, v216
	v_mov_b32_e32 v161, v217
	v_lshlrev_b32_e32 v166, 16, v158
	v_and_b32_e32 v167, 0xffff0000, v158
	v_lshlrev_b32_e32 v158, 16, v159
	v_and_b32_e32 v159, 0xffff0000, v159
	v_lshlrev_b32_e32 v168, 16, v160
	v_and_b32_e32 v169, 0xffff0000, v160
	v_lshlrev_b32_e32 v160, 16, v161
	v_and_b32_e32 v161, 0xffff0000, v161
	v_pk_add_f32 v[78:79], v[78:79], v[154:155]
	v_pk_add_f32 v[76:77], v[76:77], v[162:163]
	v_pk_add_f32 v[74:75], v[74:75], v[156:157]
	v_pk_add_f32 v[72:73], v[72:73], v[164:165]
	v_pk_add_f32 v[70:71], v[70:71], v[158:159]
	v_pk_add_f32 v[68:69], v[68:69], v[166:167]
	v_pk_add_f32 v[66:67], v[66:67], v[160:161]
	v_pk_add_f32 v[64:65], v[64:65], v[168:169]
	v_mul_f32_e32 v154, v77, v77
	v_mul_f32_e32 v155, v79, v79
	v_mul_f32_e32 v156, v73, v73
	v_mul_f32_e32 v157, v75, v75
	v_mul_f32_e32 v158, v69, v69
	v_mul_f32_e32 v159, v71, v71
	v_mul_f32_e32 v160, v65, v65
	v_mul_f32_e32 v161, v67, v67
	v_fmac_f32_e32 v154, v76, v76
	v_fmac_f32_e32 v155, v78, v78
	v_fmac_f32_e32 v156, v72, v72
	v_fmac_f32_e32 v157, v74, v74
	v_fmac_f32_e32 v158, v68, v68
	v_fmac_f32_e32 v159, v70, v70
	v_fmac_f32_e32 v160, v64, v64
	v_fmac_f32_e32 v161, v66, v66
	v_add_f32_e32 v154, v154, v155
	v_add_f32_e32 v155, v156, v157
	v_add_f32_e32 v156, v158, v159
	v_add_f32_e32 v157, v160, v161
	v_add_f32_e32 v154, v154, v155
	v_add_f32_e32 v155, v156, v157
	v_add_f32_e32 v154, v154, v155
	ds_bpermute_b32 v155, v186, v154
	s_waitcnt lgkmcnt(0)
	v_add_f32_e32 v154, v154, v155
	ds_bpermute_b32 v155, v187, v154
	s_and_saveexec_b64 s[36:37], vcc
	s_cbranch_execz .LBB0_1942
	v_lshlrev_b64 v[156:157], 6, v[152:153]
	v_lshl_add_u64 v[156:157], s[12:13], 0, v[156:157]
	v_lshl_add_u64 v[156:157], s[34:35], 2, v[156:157]
	s_lshl_b32 s16, s48, 2
	v_lshl_add_u64 v[156:157], v[156:157], 0, s[16:17]
	s_waitcnt lgkmcnt(0)
	v_add_f32_e32 v154, v154, v155
	global_store_dword v[156:157], v154, off sc1
.LBB0_1942:
	s_or_b64 exec, exec, s[36:37]
	v_add_u32_e32 v154, 0x80, v144
	s_waitcnt lgkmcnt(0)
	v_ashrrev_i32_e32 v155, 31, v154
	v_lshlrev_b64 v[156:157], 11, v[154:155]
	v_lshl_add_u64 v[156:157], s[14:15], 0, v[156:157]
	v_lshl_add_u64 v[160:161], v[146:147], 1, v[156:157]
	s_nop 0
	s_waitcnt vmcnt(15)
	v_mov_b32_e32 v156, v218
	v_mov_b32_e32 v157, v219
	v_mov_b32_e32 v158, v220
	v_mov_b32_e32 v159, v221
	v_lshlrev_b32_e32 v164, 16, v156
	v_and_b32_e32 v165, 0xffff0000, v156
	v_lshlrev_b32_e32 v156, 16, v157
	v_and_b32_e32 v157, 0xffff0000, v157
	v_lshlrev_b32_e32 v166, 16, v158
	v_and_b32_e32 v167, 0xffff0000, v158
	v_lshlrev_b32_e32 v158, 16, v159
	v_and_b32_e32 v159, 0xffff0000, v159
	v_mov_b32_e32 v160, v226
	v_mov_b32_e32 v161, v227
	v_mov_b32_e32 v162, v228
	v_mov_b32_e32 v163, v229
	v_lshlrev_b32_e32 v168, 16, v160
	v_and_b32_e32 v169, 0xffff0000, v160
	v_lshlrev_b32_e32 v160, 16, v161
	v_and_b32_e32 v161, 0xffff0000, v161
	v_lshlrev_b32_e32 v170, 16, v162
	v_and_b32_e32 v171, 0xffff0000, v162
	v_lshlrev_b32_e32 v162, 16, v163
	v_and_b32_e32 v163, 0xffff0000, v163
	v_pk_add_f32 v[62:63], v[62:63], v[156:157]
	v_pk_add_f32 v[60:61], v[60:61], v[164:165]
	v_pk_add_f32 v[58:59], v[58:59], v[158:159]
	v_pk_add_f32 v[56:57], v[56:57], v[166:167]
	v_pk_add_f32 v[54:55], v[54:55], v[160:161]
	v_pk_add_f32 v[52:53], v[52:53], v[168:169]
	v_pk_add_f32 v[50:51], v[50:51], v[162:163]
	v_pk_add_f32 v[48:49], v[48:49], v[170:171]
	v_mul_f32_e32 v156, v61, v61
	v_mul_f32_e32 v157, v63, v63
	v_mul_f32_e32 v158, v57, v57
	v_mul_f32_e32 v159, v59, v59
	v_mul_f32_e32 v160, v53, v53
	v_mul_f32_e32 v161, v55, v55
	v_mul_f32_e32 v162, v49, v49
	v_mul_f32_e32 v163, v51, v51
	v_fmac_f32_e32 v156, v60, v60
	v_fmac_f32_e32 v157, v62, v62
	v_fmac_f32_e32 v158, v56, v56
	v_fmac_f32_e32 v159, v58, v58
	v_fmac_f32_e32 v160, v52, v52
	v_fmac_f32_e32 v161, v54, v54
	v_fmac_f32_e32 v162, v48, v48
	v_fmac_f32_e32 v163, v50, v50
	v_add_f32_e32 v156, v156, v157
	v_add_f32_e32 v157, v158, v159
	v_add_f32_e32 v158, v160, v161
	v_add_f32_e32 v159, v162, v163
	v_add_f32_e32 v156, v156, v157
	v_add_f32_e32 v157, v158, v159
	v_add_f32_e32 v156, v156, v157
	ds_bpermute_b32 v157, v186, v156
	s_waitcnt lgkmcnt(0)
	v_add_f32_e32 v156, v156, v157
	ds_bpermute_b32 v157, v187, v156
	s_and_saveexec_b64 s[36:37], vcc
	s_cbranch_execz .LBB0_1944
	v_lshlrev_b64 v[158:159], 6, v[154:155]
	v_lshl_add_u64 v[158:159], s[12:13], 0, v[158:159]
	v_lshl_add_u64 v[158:159], s[34:35], 2, v[158:159]
	s_lshl_b32 s16, s48, 2
	v_lshl_add_u64 v[158:159], v[158:159], 0, s[16:17]
	s_waitcnt lgkmcnt(0)
	v_add_f32_e32 v156, v156, v157
	global_store_dword v[158:159], v156, off sc1
.LBB0_1944:
	s_or_b64 exec, exec, s[36:37]
	v_add_u32_e32 v156, 0x90, v144
	s_waitcnt lgkmcnt(0)
	v_ashrrev_i32_e32 v157, 31, v156
	v_lshlrev_b64 v[158:159], 11, v[156:157]
	v_lshl_add_u64 v[158:159], s[14:15], 0, v[158:159]
	v_lshl_add_u64 v[162:163], v[146:147], 1, v[158:159]
	s_nop 0
	s_waitcnt vmcnt(15)
	v_mov_b32_e32 v158, v230
	v_mov_b32_e32 v159, v231
	v_mov_b32_e32 v160, v232
	v_mov_b32_e32 v161, v233
	v_lshlrev_b32_e32 v166, 16, v158
	v_and_b32_e32 v167, 0xffff0000, v158
	v_lshlrev_b32_e32 v158, 16, v159
	v_and_b32_e32 v159, 0xffff0000, v159
	v_lshlrev_b32_e32 v168, 16, v160
	v_and_b32_e32 v169, 0xffff0000, v160
	v_lshlrev_b32_e32 v160, 16, v161
	v_and_b32_e32 v161, 0xffff0000, v161
	v_mov_b32_e32 v162, v234
	v_mov_b32_e32 v163, v235
	v_mov_b32_e32 v164, v236
	v_mov_b32_e32 v165, v237
	v_lshlrev_b32_e32 v170, 16, v162
	v_and_b32_e32 v171, 0xffff0000, v162
	v_lshlrev_b32_e32 v162, 16, v163
	v_and_b32_e32 v163, 0xffff0000, v163
	v_lshlrev_b32_e32 v172, 16, v164
	v_and_b32_e32 v173, 0xffff0000, v164
	v_lshlrev_b32_e32 v164, 16, v165
	v_and_b32_e32 v165, 0xffff0000, v165
	v_pk_add_f32 v[46:47], v[46:47], v[158:159]
	v_pk_add_f32 v[44:45], v[44:45], v[166:167]
	v_pk_add_f32 v[42:43], v[42:43], v[160:161]
	v_pk_add_f32 v[40:41], v[40:41], v[168:169]
	v_pk_add_f32 v[38:39], v[38:39], v[162:163]
	v_pk_add_f32 v[36:37], v[36:37], v[170:171]
	v_pk_add_f32 v[34:35], v[34:35], v[164:165]
	v_pk_add_f32 v[32:33], v[32:33], v[172:173]
	v_mul_f32_e32 v158, v45, v45
	v_mul_f32_e32 v159, v47, v47
	v_mul_f32_e32 v160, v41, v41
	v_mul_f32_e32 v161, v43, v43
	v_mul_f32_e32 v162, v37, v37
	v_mul_f32_e32 v163, v39, v39
	v_mul_f32_e32 v164, v33, v33
	v_mul_f32_e32 v165, v35, v35
	v_fmac_f32_e32 v158, v44, v44
	v_fmac_f32_e32 v159, v46, v46
	v_fmac_f32_e32 v160, v40, v40
	v_fmac_f32_e32 v161, v42, v42
	v_fmac_f32_e32 v162, v36, v36
	v_fmac_f32_e32 v163, v38, v38
	v_fmac_f32_e32 v164, v32, v32
	v_fmac_f32_e32 v165, v34, v34
	v_add_f32_e32 v158, v158, v159
	v_add_f32_e32 v159, v160, v161
	v_add_f32_e32 v160, v162, v163
	v_add_f32_e32 v161, v164, v165
	v_add_f32_e32 v158, v158, v159
	v_add_f32_e32 v159, v160, v161
	v_add_f32_e32 v158, v158, v159
	ds_bpermute_b32 v159, v186, v158
	s_waitcnt lgkmcnt(0)
	v_add_f32_e32 v158, v158, v159
	ds_bpermute_b32 v159, v187, v158
	s_and_saveexec_b64 s[36:37], vcc
	s_cbranch_execz .LBB0_1946
	v_lshlrev_b64 v[160:161], 6, v[156:157]
	v_lshl_add_u64 v[160:161], s[12:13], 0, v[160:161]
	v_lshl_add_u64 v[160:161], s[34:35], 2, v[160:161]
	s_lshl_b32 s16, s48, 2
	v_lshl_add_u64 v[160:161], v[160:161], 0, s[16:17]
	s_waitcnt lgkmcnt(0)
	v_add_f32_e32 v158, v158, v159
	global_store_dword v[160:161], v158, off sc1
.LBB0_1946:
	s_or_b64 exec, exec, s[36:37]
	v_add_u32_e32 v158, 0xa0, v144
	s_waitcnt lgkmcnt(0)
	v_ashrrev_i32_e32 v159, 31, v158
	v_lshlrev_b64 v[160:161], 11, v[158:159]
	v_lshl_add_u64 v[160:161], s[14:15], 0, v[160:161]
	v_lshl_add_u64 v[164:165], v[146:147], 1, v[160:161]
	s_nop 0
	s_waitcnt vmcnt(15)
	v_mov_b32_e32 v160, v238
	v_mov_b32_e32 v161, v239
	v_mov_b32_e32 v162, v240
	v_mov_b32_e32 v163, v241
	v_lshlrev_b32_e32 v168, 16, v160
	v_and_b32_e32 v169, 0xffff0000, v160
	v_lshlrev_b32_e32 v160, 16, v161
	v_and_b32_e32 v161, 0xffff0000, v161
	v_lshlrev_b32_e32 v170, 16, v162
	v_and_b32_e32 v171, 0xffff0000, v162
	v_lshlrev_b32_e32 v162, 16, v163
	v_and_b32_e32 v163, 0xffff0000, v163
	v_mov_b32_e32 v164, v242
	v_mov_b32_e32 v165, v243
	v_mov_b32_e32 v166, v244
	v_mov_b32_e32 v167, v245
	v_lshlrev_b32_e32 v172, 16, v164
	v_and_b32_e32 v173, 0xffff0000, v164
	v_lshlrev_b32_e32 v164, 16, v165
	v_and_b32_e32 v165, 0xffff0000, v165
	v_lshlrev_b32_e32 v174, 16, v166
	v_and_b32_e32 v175, 0xffff0000, v166
	v_lshlrev_b32_e32 v166, 16, v167
	v_and_b32_e32 v167, 0xffff0000, v167
	v_pk_add_f32 v[30:31], v[30:31], v[160:161]
	v_pk_add_f32 v[28:29], v[28:29], v[168:169]
	v_pk_add_f32 v[26:27], v[26:27], v[162:163]
	v_pk_add_f32 v[24:25], v[24:25], v[170:171]
	v_pk_add_f32 v[22:23], v[22:23], v[164:165]
	v_pk_add_f32 v[20:21], v[20:21], v[172:173]
	v_pk_add_f32 v[18:19], v[18:19], v[166:167]
	v_pk_add_f32 v[16:17], v[16:17], v[174:175]
	v_mul_f32_e32 v160, v29, v29
	v_mul_f32_e32 v161, v31, v31
	v_mul_f32_e32 v162, v25, v25
	v_mul_f32_e32 v163, v27, v27
	v_mul_f32_e32 v164, v21, v21
	v_mul_f32_e32 v165, v23, v23
	v_mul_f32_e32 v166, v17, v17
	v_mul_f32_e32 v167, v19, v19
	v_fmac_f32_e32 v160, v28, v28
	v_fmac_f32_e32 v161, v30, v30
	v_fmac_f32_e32 v162, v24, v24
	v_fmac_f32_e32 v163, v26, v26
	v_fmac_f32_e32 v164, v20, v20
	v_fmac_f32_e32 v165, v22, v22
	v_fmac_f32_e32 v166, v16, v16
	v_fmac_f32_e32 v167, v18, v18
	v_add_f32_e32 v160, v160, v161
	v_add_f32_e32 v161, v162, v163
	v_add_f32_e32 v162, v164, v165
	v_add_f32_e32 v163, v166, v167
	v_add_f32_e32 v160, v160, v161
	v_add_f32_e32 v161, v162, v163
	v_add_f32_e32 v160, v160, v161
	ds_bpermute_b32 v161, v186, v160
	s_waitcnt lgkmcnt(0)
	v_add_f32_e32 v160, v160, v161
	ds_bpermute_b32 v161, v187, v160
	s_and_saveexec_b64 s[36:37], vcc
	s_cbranch_execz .LBB0_1948
	v_lshlrev_b64 v[162:163], 6, v[158:159]
	v_lshl_add_u64 v[162:163], s[12:13], 0, v[162:163]
	v_lshl_add_u64 v[162:163], s[34:35], 2, v[162:163]
	s_lshl_b32 s16, s48, 2
	v_lshl_add_u64 v[162:163], v[162:163], 0, s[16:17]
	s_waitcnt lgkmcnt(0)
	v_add_f32_e32 v160, v160, v161
	global_store_dword v[162:163], v160, off sc1
.LBB0_1948:
	s_or_b64 exec, exec, s[36:37]
	v_add_u32_e32 v160, 0xb0, v144
	s_waitcnt lgkmcnt(0)
	v_ashrrev_i32_e32 v161, 31, v160
	v_lshlrev_b64 v[162:163], 11, v[160:161]
	v_lshl_add_u64 v[162:163], s[14:15], 0, v[162:163]
	v_lshl_add_u64 v[166:167], v[146:147], 1, v[162:163]
	s_nop 0
	s_waitcnt vmcnt(15)
	v_mov_b32_e32 v162, v246
	v_mov_b32_e32 v163, v247
	v_mov_b32_e32 v164, v248
	v_mov_b32_e32 v165, v249
	v_lshlrev_b32_e32 v170, 16, v162
	v_and_b32_e32 v171, 0xffff0000, v162
	v_lshlrev_b32_e32 v162, 16, v163
	v_and_b32_e32 v163, 0xffff0000, v163
	v_lshlrev_b32_e32 v172, 16, v164
	v_and_b32_e32 v173, 0xffff0000, v164
	v_lshlrev_b32_e32 v164, 16, v165
	v_and_b32_e32 v165, 0xffff0000, v165
	v_mov_b32_e32 v166, v180
	v_mov_b32_e32 v167, v181
	v_mov_b32_e32 v168, v182
	v_mov_b32_e32 v169, v183
	v_lshlrev_b32_e32 v188, 16, v166
	v_and_b32_e32 v189, 0xffff0000, v166
	v_lshlrev_b32_e32 v166, 16, v167
	v_and_b32_e32 v167, 0xffff0000, v167
	v_lshlrev_b32_e32 v190, 16, v168
	v_and_b32_e32 v191, 0xffff0000, v168
	v_lshlrev_b32_e32 v192, 16, v169
	v_and_b32_e32 v193, 0xffff0000, v169
	v_pk_add_f32 v[174:175], v[14:15], v[162:163]
	v_pk_add_f32 v[176:177], v[12:13], v[170:171]
	v_pk_add_f32 v[170:171], v[10:11], v[164:165]
	v_pk_add_f32 v[172:173], v[8:9], v[172:173]
	v_pk_add_f32 v[164:165], v[6:7], v[166:167]
	v_pk_add_f32 v[168:169], v[4:5], v[188:189]
	v_pk_add_f32 v[162:163], v[2:3], v[192:193]
	v_pk_add_f32 v[166:167], v[0:1], v[190:191]
	v_mul_f32_e32 v0, v177, v177
	v_mul_f32_e32 v1, v175, v175
	v_mul_f32_e32 v2, v173, v173
	v_mul_f32_e32 v3, v171, v171
	v_mul_f32_e32 v4, v169, v169
	v_mul_f32_e32 v5, v165, v165
	v_mul_f32_e32 v6, v167, v167
	v_mul_f32_e32 v7, v163, v163
	v_fmac_f32_e32 v0, v176, v176
	v_fmac_f32_e32 v1, v174, v174
	v_fmac_f32_e32 v2, v172, v172
	v_fmac_f32_e32 v3, v170, v170
	v_fmac_f32_e32 v4, v168, v168
	v_fmac_f32_e32 v5, v164, v164
	v_fmac_f32_e32 v6, v166, v166
	v_fmac_f32_e32 v7, v162, v162
	v_add_f32_e32 v0, v0, v1
	v_add_f32_e32 v1, v2, v3
	v_add_f32_e32 v2, v4, v5
	v_add_f32_e32 v3, v6, v7
	v_add_f32_e32 v0, v0, v1
	v_add_f32_e32 v1, v2, v3
	v_add_f32_e32 v0, v0, v1
	ds_bpermute_b32 v1, v186, v0
	s_waitcnt lgkmcnt(0)
	v_add_f32_e32 v0, v0, v1
	ds_bpermute_b32 v1, v187, v0
	s_and_saveexec_b64 s[36:37], vcc
	s_cbranch_execz .LBB0_1950
	v_lshlrev_b64 v[2:3], 6, v[160:161]
	v_lshl_add_u64 v[2:3], s[12:13], 0, v[2:3]
	v_lshl_add_u64 v[2:3], s[34:35], 2, v[2:3]
	s_lshl_b32 s16, s48, 2
	v_lshl_add_u64 v[2:3], v[2:3], 0, s[16:17]
	s_waitcnt lgkmcnt(0)
	v_add_f32_e32 v0, v0, v1
	global_store_dword v[2:3], v0, off sc1
